# LN (ln2 variant) prompt loop: next-iteration rows prefetched to L2
# baseline (speedup 1.0000x reference)
; __device__ __forceinline__ void ln_row_out(float* x0, float* x1, const float* w0, const float* w1, const float* b0, const float* b1, bf16* XB, float* fout, int m, int lane) {
;     float s = 0.f;
; #pragma unroll
;     for (int i = 0; i < 8; ++i) s += x0[i] + x1[i];
;     const float mean = wave_sum(s) * (1.0f / 1024.0f); float q = 0.f;
; #pragma unroll
;     for (int i = 0; i < 8; ++i) { x0[i] -= mean; x1[i] -= mean; q += x0[i] * x0[i] + x1[i] * x1[i]; }
;     const float rstd = rsqrtf(wave_sum(q) * (1.0f / 1024.0f) + LN_EPS);
; #pragma unroll
;     for (int i = 0; i < 8; ++i) { x0[i] = x0[i] * rstd * w0[i] + b0[i]; x1[i] = x1[i] * rstd * w1[i] + b1[i]; }
;     if (fout) {
;         float* fo = fout + (size_t)m * 1024 + 8 * lane;
;         *(f32x4*)(fo) = (f32x4){x0[0], x0[1], x0[2], x0[3]}; *(f32x4*)(fo + 4) = (f32x4){x0[4], x0[5], x0[6], x0[7]};
;         *(f32x4*)(fo + 512) = (f32x4){x1[0], x1[1], x1[2], x1[3]}; *(f32x4*)(fo + 516) = (f32x4){x1[4], x1[5], x1[6], x1[7]};
;     } else {
;         *(v4u*)(XB + (size_t)m * 1024 + 8 * lane) = pack8(x0); *(v4u*)(XB + (size_t)m * 1024 + 512 + 8 * lane) = pack8(x1);
;     }
; __device__ __forceinline__ void ln_phase(const Args& a, const float* w, const float* b, float* fout, int ns) {
;     ...
;     for (int mb = gw; mb < MP; mb += 4 * ngw) {
;         v4u r0[4], r1[4];
; #pragma unroll
;         for (int j = 0; j < 4; ++j) { const int m = mb + j * ngw; const int mc = m < MP ? m : mb;
;             r0[j] = *(const v4u*)(Z + (size_t)mc * 1024 + 8 * lane); r1[j] = *(const v4u*)(Z + (size_t)mc * 1024 + 512 + 8 * lane); }
; #pragma unroll
;         for (int j = 0; j < 4; ++j) {
;             const int m = mb + j * ngw;
;             float x0[8], x1[8];
;             unpack8(r0[j], x0); unpack8(r1[j], x1);
;             if (m < MP) ln_row_out(x0, x1, w0, w1, b0, b1, XB, fout, m, lane);
.LBB0_289:
	v_add_u32_e32 v84, s10, v92
	v_cmp_gt_i32_e64 s[44:45], s52, v84
	v_add_u32_e32 v88, s3, v92
	v_cmp_gt_i32_e64 s[40:41], s52, v88
	v_cndmask_b32_e64 v34, v92, v84, s[44:45]
	v_ashrrev_i32_e32 v35, 31, v34
	v_lshlrev_b64 v[34:35], 11, v[34:35]
	v_lshl_add_u64 v[34:35], v[80:81], 0, v[34:35]
	global_load_dwordx4 v[54:57], v[34:35], off
	global_load_dwordx4 v[50:53], v[34:35], off offset:1024
	v_cndmask_b32_e64 v34, v92, v88, s[40:41]
	v_ashrrev_i32_e32 v35, 31, v34
	v_lshlrev_b64 v[34:35], 11, v[34:35]
	v_add_u32_e32 v86, s14, v92
	v_lshl_add_u64 v[34:35], v[80:81], 0, v[34:35]
	v_cmp_gt_i32_e64 s[38:39], s52, v86
	global_load_dwordx4 v[46:49], v[34:35], off
	global_load_dwordx4 v[42:45], v[34:35], off offset:1024
	v_cndmask_b32_e64 v34, v92, v86, s[38:39]
	v_ashrrev_i32_e32 v93, 31, v92
	v_ashrrev_i32_e32 v35, 31, v34
	v_lshlrev_b64 v[90:91], 11, v[92:93]
	v_lshlrev_b64 v[34:35], 11, v[34:35]
	v_lshl_add_u64 v[34:35], v[80:81], 0, v[34:35]
	v_lshl_add_u64 v[62:63], v[80:81], 0, v[90:91]
	global_load_dwordx4 v[38:41], v[34:35], off
	s_nop 0
	global_load_dwordx4 v[34:37], v[34:35], off offset:1024
	s_nop 0
	global_load_dwordx4 v[58:61], v[62:63], off offset:1024
	s_nop 0
	global_load_dwordx4 v[62:65], v[62:63], off
	s_lshl_b32 s4, s64, 11
	s_mov_b32 s5, 0
	s_lshl_b32 s6, s64, 13
	s_mov_b32 s7, 0
	s_mov_b32 m0, 0x20100
	v_lshl_add_u64 v[108:109], v[80:81], 0, v[90:91]
	v_lshl_add_u64 v[108:109], v[108:109], 0, s[6:7]
	global_load_lds_dword v[108:109], off
	global_load_lds_dword v[108:109], off offset:1024
	v_lshl_add_u64 v[108:109], v[108:109], 0, s[4:5]
	global_load_lds_dword v[108:109], off
	global_load_lds_dword v[108:109], off offset:1024
	v_lshl_add_u64 v[108:109], v[108:109], 0, s[4:5]
	global_load_lds_dword v[108:109], off
	global_load_lds_dword v[108:109], off offset:1024
	v_lshl_add_u64 v[108:109], v[108:109], 0, s[4:5]
	global_load_lds_dword v[108:109], off
	global_load_lds_dword v[108:109], off offset:1024
	s_waitcnt vmcnt(9)
	v_lshlrev_b32_e32 v70, 16, v58
	s_waitcnt vmcnt(8)
	v_lshlrev_b32_e32 v66, 16, v62
	v_and_b32_e32 v67, 0xffff0000, v62
	v_and_b32_e32 v71, 0xffff0000, v58
	v_pk_add_f32 v[72:73], v[70:71], v[66:67]
	v_lshlrev_b32_e32 v62, 16, v63
	v_add_f32_e32 v58, 0, v72
	v_and_b32_e32 v63, 0xffff0000, v63
	v_add_f32_e32 v77, v73, v58
	v_lshlrev_b32_e32 v58, 16, v59
	v_and_b32_e32 v59, 0xffff0000, v59
	v_pk_add_f32 v[72:73], v[58:59], v[62:63]
	v_lshlrev_b32_e32 v68, 16, v64
	v_add_f32_e32 v72, v72, v77
	v_and_b32_e32 v69, 0xffff0000, v64
	v_add_f32_e32 v77, v73, v72
	v_lshlrev_b32_e32 v72, 16, v60
	v_and_b32_e32 v73, 0xffff0000, v60
	v_pk_add_f32 v[100:101], v[72:73], v[68:69]
	v_lshlrev_b32_e32 v64, 16, v65
	v_add_f32_e32 v60, v100, v77
	v_and_b32_e32 v65, 0xffff0000, v65
	v_add_f32_e32 v77, v101, v60
	v_lshlrev_b32_e32 v60, 16, v61
	v_and_b32_e32 v61, 0xffff0000, v61
	v_pk_add_f32 v[100:101], v[60:61], v[64:65]
	s_nop 0
	v_add_f32_e32 v77, v100, v77
	v_add_f32_e32 v77, v101, v77
	ds_bpermute_b32 v85, v94, v77
	s_waitcnt lgkmcnt(0)
	v_add_f32_e32 v77, v77, v85
	ds_bpermute_b32 v85, v95, v77
	s_waitcnt lgkmcnt(0)
	v_add_f32_e32 v77, v77, v85
	ds_bpermute_b32 v85, v96, v77
	s_waitcnt lgkmcnt(0)
	v_add_f32_e32 v77, v77, v85
	ds_bpermute_b32 v85, v97, v77
	s_waitcnt lgkmcnt(0)
	v_add_f32_e32 v77, v77, v85
	ds_bpermute_b32 v85, v98, v77
	s_waitcnt lgkmcnt(0)
	v_add_f32_e32 v77, v77, v85
	ds_bpermute_b32 v85, v99, v77
	s_waitcnt lgkmcnt(0)
	v_add_f32_e32 v77, v77, v85
	v_mul_f32_e32 v100, 0x3a800000, v77
	v_pk_add_f32 v[66:67], v[66:67], v[100:101] op_sel_hi:[1,0] neg_lo:[0,1] neg_hi:[0,1]
	v_pk_add_f32 v[70:71], v[70:71], v[100:101] op_sel_hi:[1,0] neg_lo:[0,1] neg_hi:[0,1]
	v_pk_mul_f32 v[102:103], v[66:67], v[66:67]
	v_pk_add_f32 v[62:63], v[62:63], v[100:101] op_sel_hi:[1,0] neg_lo:[0,1] neg_hi:[0,1]
	v_pk_fma_f32 v[102:103], v[70:71], v[70:71], v[102:103]
	v_pk_mul_f32 v[104:105], v[62:63], v[62:63]
	v_pk_add_f32 v[106:107], v[58:59], v[100:101] op_sel_hi:[1,0] neg_lo:[0,1] neg_hi:[0,1]
	v_add_f32_e32 v77, v102, v103
	v_pk_fma_f32 v[58:59], v[106:107], v[106:107], v[104:105]
	v_pk_add_f32 v[104:105], v[68:69], v[100:101] op_sel_hi:[1,0] neg_lo:[0,1] neg_hi:[0,1]
	v_pk_add_f32 v[72:73], v[72:73], v[100:101] op_sel_hi:[1,0] neg_lo:[0,1] neg_hi:[0,1]
	v_pk_mul_f32 v[68:69], v[104:105], v[104:105]
	v_add_f32_e32 v58, v58, v77
	v_pk_fma_f32 v[68:69], v[72:73], v[72:73], v[68:69]
	v_pk_add_f32 v[64:65], v[64:65], v[100:101] op_sel_hi:[1,0] neg_lo:[0,1] neg_hi:[0,1]
	v_add_f32_e32 v58, v59, v58
	v_pk_add_f32 v[100:101], v[60:61], v[100:101] op_sel_hi:[1,0] neg_lo:[0,1] neg_hi:[0,1]
	v_pk_mul_f32 v[60:61], v[64:65], v[64:65]
	v_add_f32_e32 v58, v68, v58
	v_pk_fma_f32 v[60:61], v[100:101], v[100:101], v[60:61]
	v_add_f32_e32 v58, v69, v58
	v_add_f32_e32 v58, v60, v58
	v_add_f32_e32 v58, v61, v58
	ds_bpermute_b32 v59, v94, v58
	v_cndmask_b32_e64 v77, 0, 1, s[28:29]
	v_cmp_ne_u32_e64 s[42:43], 1, v77
	s_waitcnt lgkmcnt(0)
	v_add_f32_e32 v58, v58, v59
	ds_bpermute_b32 v59, v95, v58
	s_waitcnt lgkmcnt(0)
	v_add_f32_e32 v58, v58, v59
	ds_bpermute_b32 v59, v96, v58
	s_waitcnt lgkmcnt(0)
	v_add_f32_e32 v58, v58, v59
	ds_bpermute_b32 v59, v97, v58
	s_waitcnt lgkmcnt(0)
	v_add_f32_e32 v58, v58, v59
	ds_bpermute_b32 v59, v98, v58
	s_waitcnt lgkmcnt(0)
	v_add_f32_e32 v58, v58, v59
	ds_bpermute_b32 v59, v99, v58
	s_waitcnt lgkmcnt(0)
	v_add_f32_e32 v58, v58, v59
	v_fmamk_f32 v58, v58, 0x3a800000, v151
	v_cmp_gt_f32_e32 vcc, s50, v58
	v_mul_f32_e32 v59, 0x4b800000, v58
	s_nop 0
	v_cndmask_b32_e32 v58, v58, v59, vcc
	v_rsq_f32_e32 v58, v58
	s_nop 0
	v_mul_f32_e32 v59, 0x45800000, v58
	v_cndmask_b32_e32 v102, v58, v59, vcc
	v_pk_mul_f32 v[58:59], v[66:67], v[102:103] op_sel_hi:[1,0]
	v_pk_mul_f32 v[60:61], v[70:71], v[102:103] op_sel_hi:[1,0]
	v_pk_fma_f32 v[66:67], v[6:7], v[58:59], v[22:23]
	v_pk_fma_f32 v[58:59], v[14:15], v[60:61], v[30:31]
	v_pk_mul_f32 v[60:61], v[62:63], v[102:103] op_sel_hi:[1,0]
	v_pk_mul_f32 v[62:63], v[106:107], v[102:103] op_sel_hi:[1,0]
	v_pk_fma_f32 v[68:69], v[8:9], v[60:61], v[24:25]
	v_pk_fma_f32 v[60:61], v[16:17], v[62:63], v[32:33]
	v_pk_mul_f32 v[62:63], v[104:105], v[102:103] op_sel_hi:[1,0]
	v_pk_mul_f32 v[72:73], v[72:73], v[102:103] op_sel_hi:[1,0]
	v_pk_mul_f32 v[64:65], v[64:65], v[102:103] op_sel_hi:[1,0]
	v_pk_mul_f32 v[100:101], v[100:101], v[102:103] op_sel_hi:[1,0]
	v_pk_fma_f32 v[70:71], v[2:3], v[62:63], v[18:19]
	v_pk_fma_f32 v[62:63], v[10:11], v[72:73], v[26:27]
	v_pk_fma_f32 v[72:73], v[4:5], v[64:65], v[20:21]
	v_pk_fma_f32 v[64:65], v[12:13], v[100:101], v[28:29]
	s_andn2_b64 vcc, exec, s[28:29]
	s_cbranch_vccnz .LBB0_303
	v_lshlrev_b64 v[92:93], 12, v[92:93]
	v_lshl_add_u64 v[92:93], v[78:79], 0, v[92:93]
	global_store_dwordx4 v[92:93], v[66:69], off
	global_store_dwordx4 v[92:93], v[70:73], off offset:16
	global_store_dwordx4 v[92:93], v[58:61], off offset:2048
	global_store_dwordx4 v[92:93], v[62:65], off offset:2064
	s_cbranch_execnz .LBB0_292
